# FFN-in: first K iteration peeled with SrcC=0 MFMAs, 128 accumulator v_mov zeroing removed (on top of B0 pre-read)
# speedup vs baseline: 1.0226x; 1.0077x over previous
.LBB0_556:
	v_mov_b64_e32 v[0:1], 0x420
	s_ashr_i32 s49, s48, 31
	v_cmp_lt_i64_e32 vcc, s[50:51], v[0:1]
	s_lshl_b64 s[50:51], s[48:49], 19
	s_add_u32 s50, s4, s50
	s_addc_u32 s51, s5, s51
	s_and_b64 s[52:53], vcc, exec
	s_cselect_b32 s49, s51, s59
	s_cselect_b32 s67, s50, s58
	s_ashr_i32 s47, s46, 31
	s_lshl_b64 s[52:53], s[46:47], 19
	s_add_u32 s52, s10, s52
	s_addc_u32 s53, s11, s53
	s_and_b64 s[62:63], vcc, exec
	s_cselect_b32 s47, s53, s61
	s_cselect_b32 s68, s52, s60
	s_add_u32 s58, s58, 0x40080
	s_addc_u32 s59, s59, 0
	s_add_u32 s69, s60, 0x100
	s_addc_u32 s70, s61, 0
	s_mov_b32 s71, -2
	v_add_u32_e32 v96, 0x10000, v193
	ds_read_b128 v[80:83], v96
	ds_read_b128 v[88:91], v96 offset:1024
	ds_read_b128 v[102:105], v96 offset:2048
	ds_read_b128 v[106:109], v96 offset:3072
	s_add_u32 s60, s58, 0xfffc0080
	s_addc_u32 s61, s59, -1
	s_add_i32 s72, 0, 0x10000
	v_add_u32_e32 v96, s72, v193
	s_cmp_eq_u32 s71, 12
	s_cselect_b32 s63, s49, s61
	s_cselect_b32 s62, s67, s60
	s_cselect_b32 s61, s47, s70
	s_cselect_b32 s60, s68, s69
	s_add_i32 m0, s27, 0xc000
	ds_read_b128 v[160:163], v195
	ds_read_b128 v[164:167], v195 offset:1024
	ds_read_b128 v[168:171], v195 offset:2048
	ds_read_b128 v[172:175], v195 offset:3072
	ds_read_b128 v[182:185], v195 offset:4096
	ds_read_b128 v[186:189], v195 offset:5120
	ds_read_b128 v[196:199], v195 offset:6144
	ds_read_b128 v[200:203], v195 offset:7168
	global_load_lds_dwordx4 v156, s[58:59]
	s_add_i32 m0, s27, 0xe000
	s_nop 0
	global_load_lds_dwordx4 v158, s[58:59]
	s_setprio 1
	s_barrier
	s_waitcnt lgkmcnt(0)
	v_mfma_f32_16x16x32_bf16 v[142:145], v[80:83], v[160:163], 0
	v_mfma_f32_16x16x32_bf16 v[138:141], v[102:105], v[160:163], 0
	v_mfma_f32_16x16x32_bf16 v[126:129], v[80:83], v[168:171], 0
	v_mfma_f32_16x16x32_bf16 v[122:125], v[102:105], v[168:171], 0
	v_mfma_f32_16x16x32_bf16 v[110:113], v[80:83], v[182:185], 0
	v_mfma_f32_16x16x32_bf16 v[98:101], v[102:105], v[182:185], 0
	v_mfma_f32_16x16x32_bf16 v[76:79], v[80:83], v[196:199], 0
	v_mfma_f32_16x16x32_bf16 v[72:75], v[102:105], v[196:199], 0
	v_mfma_f32_16x16x32_bf16 v[142:145], v[88:91], v[164:167], v[142:145]
	v_mfma_f32_16x16x32_bf16 v[138:141], v[106:109], v[164:167], v[138:141]
	v_mfma_f32_16x16x32_bf16 v[126:129], v[88:91], v[172:175], v[126:129]
	v_mfma_f32_16x16x32_bf16 v[122:125], v[106:109], v[172:175], v[122:125]
	v_mfma_f32_16x16x32_bf16 v[110:113], v[88:91], v[186:189], v[110:113]
	v_mfma_f32_16x16x32_bf16 v[98:101], v[106:109], v[186:189], v[98:101]
	v_mfma_f32_16x16x32_bf16 v[76:79], v[88:91], v[200:203], v[76:79]
	v_mfma_f32_16x16x32_bf16 v[72:75], v[106:109], v[200:203], v[72:75]
	s_barrier
	s_setprio 0
	s_add_i32 s76, 0, 0x14000
	s_add_i32 s72, s72, s18
	v_add_u32_e32 v96, s76, v193
	v_lshl_add_u64 v[176:177], s[60:61], 0, v[150:151]
	s_mov_b32 m0, s72
	ds_read_b128 v[224:227], v96
	ds_read_b128 v[228:231], v96 offset:1024
	ds_read_b128 v[232:235], v96 offset:2048
	ds_read_b128 v[236:239], v96 offset:3072
	global_load_lds_dwordx4 v150, s[60:61]
	v_lshl_add_u64 v[190:191], s[60:61], 0, v[146:147]
	s_add_i32 m0, s72, 0x2000
	s_nop 0
	global_load_lds_dwordx4 v146, s[60:61]
	s_setprio 1
	s_barrier
	s_waitcnt lgkmcnt(0)
	v_mfma_f32_16x16x32_bf16 v[134:137], v[224:227], v[160:163], 0
	v_mfma_f32_16x16x32_bf16 v[130:133], v[232:235], v[160:163], 0
	v_mfma_f32_16x16x32_bf16 v[118:121], v[224:227], v[168:171], 0
	s_mov_b32 m0, s27
	v_mfma_f32_16x16x32_bf16 v[114:117], v[232:235], v[168:171], 0
	v_lshl_add_u64 v[240:241], s[62:63], 0, v[152:153]
	v_mfma_f32_16x16x32_bf16 v[92:95], v[224:227], v[182:185], 0
	v_mfma_f32_16x16x32_bf16 v[84:87], v[232:235], v[182:185], 0
	v_mfma_f32_16x16x32_bf16 v[68:71], v[224:227], v[196:199], 0
	v_mfma_f32_16x16x32_bf16 v[64:67], v[232:235], v[196:199], 0
	v_mfma_f32_16x16x32_bf16 v[134:137], v[228:231], v[164:167], v[134:137]
	v_mfma_f32_16x16x32_bf16 v[130:133], v[236:239], v[164:167], v[130:133]
	v_mfma_f32_16x16x32_bf16 v[118:121], v[228:231], v[172:175], v[118:121]
	v_mfma_f32_16x16x32_bf16 v[114:117], v[236:239], v[172:175], v[114:117]
	v_mfma_f32_16x16x32_bf16 v[92:95], v[228:231], v[186:189], v[92:95]
	v_mfma_f32_16x16x32_bf16 v[84:87], v[236:239], v[186:189], v[84:87]
	v_mfma_f32_16x16x32_bf16 v[68:71], v[228:231], v[200:203], v[68:71]
	v_mfma_f32_16x16x32_bf16 v[64:67], v[236:239], v[200:203], v[64:67]
	s_barrier
	s_setprio 0
	ds_read_b128 v[160:163], v195 offset:16384
	ds_read_b128 v[164:167], v195 offset:17408
	ds_read_b128 v[168:171], v195 offset:18432
	ds_read_b128 v[172:175], v195 offset:19456
	ds_read_b128 v[182:185], v195 offset:20480
	ds_read_b128 v[186:189], v195 offset:21504
	ds_read_b128 v[196:199], v195 offset:22528
	ds_read_b128 v[200:203], v195 offset:23552
	global_load_lds_dwordx4 v152, s[62:63]
	v_lshl_add_u64 v[242:243], s[62:63], 0, v[148:149]
	s_mov_b32 m0, s28
	s_nop 0
	global_load_lds_dwordx4 v148, s[62:63]
	s_waitcnt vmcnt(10)
	s_setprio 1
	s_barrier
	s_waitcnt lgkmcnt(0)
	v_mfma_f32_16x16x32_bf16 v[60:63], v[80:83], v[160:163], 0
	v_mfma_f32_16x16x32_bf16 v[56:59], v[102:105], v[160:163], 0
	v_mfma_f32_16x16x32_bf16 v[44:47], v[80:83], v[168:171], 0
	v_mfma_f32_16x16x32_bf16 v[40:43], v[102:105], v[168:171], 0
	v_mfma_f32_16x16x32_bf16 v[28:31], v[80:83], v[182:185], 0
	v_mfma_f32_16x16x32_bf16 v[24:27], v[102:105], v[182:185], 0
	v_mfma_f32_16x16x32_bf16 v[12:15], v[80:83], v[196:199], 0
	v_mfma_f32_16x16x32_bf16 v[8:11], v[102:105], v[196:199], 0
	v_mfma_f32_16x16x32_bf16 v[60:63], v[88:91], v[164:167], v[60:63]
	v_mfma_f32_16x16x32_bf16 v[56:59], v[106:109], v[164:167], v[56:59]
	v_mfma_f32_16x16x32_bf16 v[44:47], v[88:91], v[172:175], v[44:47]
	v_mfma_f32_16x16x32_bf16 v[40:43], v[106:109], v[172:175], v[40:43]
	v_mfma_f32_16x16x32_bf16 v[28:31], v[88:91], v[186:189], v[28:31]
	v_mfma_f32_16x16x32_bf16 v[24:27], v[106:109], v[186:189], v[24:27]
	v_mfma_f32_16x16x32_bf16 v[12:15], v[88:91], v[200:203], v[12:15]
	v_mfma_f32_16x16x32_bf16 v[8:11], v[106:109], v[200:203], v[8:11]
	s_barrier
	s_setprio 0
	v_add_u32_e32 v96, 0x18000, v193
	ds_read_b128 v[80:83], v96
	ds_read_b128 v[88:91], v96 offset:1024
	ds_read_b128 v[102:105], v96 offset:2048
	ds_read_b128 v[106:109], v96 offset:3072
	s_add_u32 s74, s60, 0x40000
	s_addc_u32 s75, s61, 0
	s_add_i32 s72, s76, s18
	s_mov_b32 m0, s72
	s_nop 0
	global_load_lds_dwordx4 v150, s[74:75]
	s_add_i32 m0, s72, 0x2000
	s_nop 0
	global_load_lds_dwordx4 v146, s[74:75]
	s_waitcnt vmcnt(6)
	s_setprio 1
	s_barrier
	v_mfma_f32_16x16x32_bf16 v[52:55], v[224:227], v[160:163], 0
	v_mfma_f32_16x16x32_bf16 v[48:51], v[232:235], v[160:163], 0
	v_mfma_f32_16x16x32_bf16 v[36:39], v[224:227], v[168:171], 0
	s_add_i32 s72, 0, 0x18000
	v_mfma_f32_16x16x32_bf16 v[32:35], v[232:235], v[168:171], 0
	v_add_u32_e32 v96, s72, v193
	v_mfma_f32_16x16x32_bf16 v[20:23], v[224:227], v[182:185], 0
	v_mfma_f32_16x16x32_bf16 v[16:19], v[232:235], v[182:185], 0
	v_mfma_f32_16x16x32_bf16 v[4:7], v[224:227], v[196:199], 0
	v_mfma_f32_16x16x32_bf16 v[0:3], v[232:235], v[196:199], 0
	v_mfma_f32_16x16x32_bf16 v[52:55], v[228:231], v[164:167], v[52:55]
	v_mfma_f32_16x16x32_bf16 v[48:51], v[236:239], v[164:167], v[48:51]
	v_mfma_f32_16x16x32_bf16 v[36:39], v[228:231], v[172:175], v[36:39]
	v_mfma_f32_16x16x32_bf16 v[32:35], v[236:239], v[172:175], v[32:35]
	v_mfma_f32_16x16x32_bf16 v[20:23], v[228:231], v[186:189], v[20:23]
	v_mfma_f32_16x16x32_bf16 v[16:19], v[236:239], v[186:189], v[16:19]
	v_mfma_f32_16x16x32_bf16 v[4:7], v[228:231], v[200:203], v[4:7]
	v_mfma_f32_16x16x32_bf16 v[0:3], v[236:239], v[200:203], v[0:3]
	s_barrier
	s_setprio 0
	s_add_u32 s62, s62, 0x40000
	s_addc_u32 s63, s63, 0
	s_mov_b32 m0, s37
	ds_read_b128 v[160:163], v195 offset:32768
	ds_read_b128 v[164:167], v195 offset:33792
	ds_read_b128 v[168:171], v195 offset:34816
	ds_read_b128 v[172:175], v195 offset:35840
	ds_read_b128 v[182:185], v195 offset:36864
	ds_read_b128 v[186:189], v195 offset:37888
	ds_read_b128 v[196:199], v195 offset:38912
	ds_read_b128 v[200:203], v195 offset:39936
	global_load_lds_dwordx4 v152, s[62:63]
	s_mov_b32 m0, s56
	s_nop 0
	global_load_lds_dwordx4 v148, s[62:63]
	s_setprio 1
	s_barrier
	s_waitcnt lgkmcnt(0)
	v_mfma_f32_16x16x32_bf16 v[142:145], v[80:83], v[160:163], v[142:145]
	v_mfma_f32_16x16x32_bf16 v[138:141], v[102:105], v[160:163], v[138:141]
	v_mfma_f32_16x16x32_bf16 v[126:129], v[80:83], v[168:171], v[126:129]
	v_mfma_f32_16x16x32_bf16 v[122:125], v[102:105], v[168:171], v[122:125]
	v_mfma_f32_16x16x32_bf16 v[110:113], v[80:83], v[182:185], v[110:113]
	v_mfma_f32_16x16x32_bf16 v[98:101], v[102:105], v[182:185], v[98:101]
	v_mfma_f32_16x16x32_bf16 v[76:79], v[80:83], v[196:199], v[76:79]
	v_mfma_f32_16x16x32_bf16 v[72:75], v[102:105], v[196:199], v[72:75]
	v_mfma_f32_16x16x32_bf16 v[142:145], v[88:91], v[164:167], v[142:145]
	v_mfma_f32_16x16x32_bf16 v[138:141], v[106:109], v[164:167], v[138:141]
	v_mfma_f32_16x16x32_bf16 v[126:129], v[88:91], v[172:175], v[126:129]
	v_mfma_f32_16x16x32_bf16 v[122:125], v[106:109], v[172:175], v[122:125]
	v_mfma_f32_16x16x32_bf16 v[110:113], v[88:91], v[186:189], v[110:113]
	v_mfma_f32_16x16x32_bf16 v[98:101], v[106:109], v[186:189], v[98:101]
	v_mfma_f32_16x16x32_bf16 v[76:79], v[88:91], v[200:203], v[76:79]
	v_mfma_f32_16x16x32_bf16 v[72:75], v[106:109], v[200:203], v[72:75]
	s_barrier
	s_setprio 0
	s_add_i32 s62, 0, 0x1c000
	s_add_i32 s63, s72, s18
	v_add_u32_e32 v96, s62, v193
	v_lshl_add_u64 v[176:177], v[176:177], 0, s[6:7]
	s_mov_b32 m0, s63
	ds_read_b128 v[224:227], v96
	ds_read_b128 v[228:231], v96 offset:1024
	ds_read_b128 v[232:235], v96 offset:2048
	ds_read_b128 v[236:239], v96 offset:3072
	global_load_lds_dwordx4 v[176:177], off
	v_lshl_add_u64 v[176:177], v[190:191], 0, s[6:7]
	s_add_i32 m0, s63, 0x2000
	s_nop 0
	global_load_lds_dwordx4 v[176:177], off
	s_setprio 1
	s_barrier
	s_waitcnt lgkmcnt(0)
	v_mfma_f32_16x16x32_bf16 v[134:137], v[224:227], v[160:163], v[134:137]
	v_mfma_f32_16x16x32_bf16 v[130:133], v[232:235], v[160:163], v[130:133]
	v_mfma_f32_16x16x32_bf16 v[118:121], v[224:227], v[168:171], v[118:121]
	s_mov_b32 m0, s64
	v_mfma_f32_16x16x32_bf16 v[114:117], v[232:235], v[168:171], v[114:117]
	v_lshl_add_u64 v[176:177], v[240:241], 0, s[6:7]
	v_mfma_f32_16x16x32_bf16 v[92:95], v[224:227], v[182:185], v[92:95]
	v_mfma_f32_16x16x32_bf16 v[84:87], v[232:235], v[182:185], v[84:87]
	v_mfma_f32_16x16x32_bf16 v[68:71], v[224:227], v[196:199], v[68:71]
	v_mfma_f32_16x16x32_bf16 v[64:67], v[232:235], v[196:199], v[64:67]
	v_mfma_f32_16x16x32_bf16 v[134:137], v[228:231], v[164:167], v[134:137]
	v_mfma_f32_16x16x32_bf16 v[130:133], v[236:239], v[164:167], v[130:133]
	v_mfma_f32_16x16x32_bf16 v[118:121], v[228:231], v[172:175], v[118:121]
	v_mfma_f32_16x16x32_bf16 v[114:117], v[236:239], v[172:175], v[114:117]
	v_mfma_f32_16x16x32_bf16 v[92:95], v[228:231], v[186:189], v[92:95]
	v_mfma_f32_16x16x32_bf16 v[84:87], v[236:239], v[186:189], v[84:87]
	v_mfma_f32_16x16x32_bf16 v[68:71], v[228:231], v[200:203], v[68:71]
	v_mfma_f32_16x16x32_bf16 v[64:67], v[236:239], v[200:203], v[64:67]
	s_barrier
	s_setprio 0
	ds_read_b128 v[160:163], v195 offset:49152
	ds_read_b128 v[164:167], v195 offset:50176
	ds_read_b128 v[168:171], v195 offset:51200
	ds_read_b128 v[172:175], v195 offset:52224
	ds_read_b128 v[182:185], v195 offset:53248
	ds_read_b128 v[186:189], v195 offset:54272
	ds_read_b128 v[196:199], v195 offset:55296
	ds_read_b128 v[200:203], v195 offset:56320
	global_load_lds_dwordx4 v[176:177], off
	v_lshl_add_u64 v[176:177], v[242:243], 0, s[6:7]
	s_mov_b32 m0, s65
	s_nop 0
	global_load_lds_dwordx4 v[176:177], off
	s_waitcnt vmcnt(10)
	s_setprio 1
	s_barrier
	s_waitcnt lgkmcnt(0)
	v_mfma_f32_16x16x32_bf16 v[60:63], v[80:83], v[160:163], v[60:63]
	v_mfma_f32_16x16x32_bf16 v[56:59], v[102:105], v[160:163], v[56:59]
	v_mfma_f32_16x16x32_bf16 v[44:47], v[80:83], v[168:171], v[44:47]
	v_mfma_f32_16x16x32_bf16 v[40:43], v[102:105], v[168:171], v[40:43]
	v_mfma_f32_16x16x32_bf16 v[28:31], v[80:83], v[182:185], v[28:31]
	v_mfma_f32_16x16x32_bf16 v[24:27], v[102:105], v[182:185], v[24:27]
	v_mfma_f32_16x16x32_bf16 v[12:15], v[80:83], v[196:199], v[12:15]
	v_mfma_f32_16x16x32_bf16 v[8:11], v[102:105], v[196:199], v[8:11]
	v_mfma_f32_16x16x32_bf16 v[60:63], v[88:91], v[164:167], v[60:63]
	v_mfma_f32_16x16x32_bf16 v[56:59], v[106:109], v[164:167], v[56:59]
	v_mfma_f32_16x16x32_bf16 v[44:47], v[88:91], v[172:175], v[44:47]
	v_mfma_f32_16x16x32_bf16 v[40:43], v[106:109], v[172:175], v[40:43]
	v_mfma_f32_16x16x32_bf16 v[28:31], v[88:91], v[186:189], v[28:31]
	v_mfma_f32_16x16x32_bf16 v[24:27], v[106:109], v[186:189], v[24:27]
	v_mfma_f32_16x16x32_bf16 v[12:15], v[88:91], v[200:203], v[12:15]
	v_mfma_f32_16x16x32_bf16 v[8:11], v[106:109], v[200:203], v[8:11]
	s_barrier
	s_setprio 0
	v_add_u32_e32 v96, 0x10000, v193
	ds_read_b128 v[80:83], v96
	ds_read_b128 v[88:91], v96 offset:1024
	ds_read_b128 v[102:105], v96 offset:2048
	ds_read_b128 v[106:109], v96 offset:3072
	s_add_u32 s60, s60, 0x40080
	s_addc_u32 s61, s61, 0
	s_add_i32 s62, s62, s18
	s_mov_b32 m0, s62
	s_nop 0
	global_load_lds_dwordx4 v150, s[60:61]
	s_add_i32 m0, s62, 0x2000
	s_nop 0
	global_load_lds_dwordx4 v146, s[60:61]
	s_waitcnt vmcnt(6)
	s_setprio 1
	s_barrier
	v_mfma_f32_16x16x32_bf16 v[52:55], v[224:227], v[160:163], v[52:55]
	v_mfma_f32_16x16x32_bf16 v[48:51], v[232:235], v[160:163], v[48:51]
	v_mfma_f32_16x16x32_bf16 v[36:39], v[224:227], v[168:171], v[36:39]
	s_add_i32 s71, s71, 2
	v_mfma_f32_16x16x32_bf16 v[32:35], v[232:235], v[168:171], v[32:35]
	s_add_u32 s58, s58, 0x100
	v_mfma_f32_16x16x32_bf16 v[20:23], v[224:227], v[182:185], v[20:23]
	s_addc_u32 s59, s59, 0
	v_mfma_f32_16x16x32_bf16 v[16:19], v[232:235], v[182:185], v[16:19]
	s_add_u32 s69, s69, 0x100
	v_mfma_f32_16x16x32_bf16 v[4:7], v[224:227], v[196:199], v[4:7]
	s_addc_u32 s70, s70, 0
	v_mfma_f32_16x16x32_bf16 v[0:3], v[232:235], v[196:199], v[0:3]
	s_cmp_gt_u32 s71, 13
	v_mfma_f32_16x16x32_bf16 v[52:55], v[228:231], v[164:167], v[52:55]
	v_mfma_f32_16x16x32_bf16 v[48:51], v[236:239], v[164:167], v[48:51]
	v_mfma_f32_16x16x32_bf16 v[36:39], v[228:231], v[172:175], v[36:39]
	v_mfma_f32_16x16x32_bf16 v[32:35], v[236:239], v[172:175], v[32:35]
	v_mfma_f32_16x16x32_bf16 v[20:23], v[228:231], v[186:189], v[20:23]
	v_mfma_f32_16x16x32_bf16 v[16:19], v[236:239], v[186:189], v[16:19]
	v_mfma_f32_16x16x32_bf16 v[4:7], v[228:231], v[200:203], v[4:7]
	v_mfma_f32_16x16x32_bf16 v[0:3], v[236:239], v[200:203], v[0:3]
	s_barrier
	s_setprio 0

.Lhl_exit_tramp:
	s_branch .LBB0_1191
